# P4 compress item: the MFMA loop issues all loads of its four k-steps up front into free registers and uses counted waits (was two full vmcnt(0) round trips per k-step)
# speedup vs baseline: 1.0554x; 1.0110x over previous
.LBB0_635:
	s_add_i32 s15, s13, -1
	s_lshr_b32 s19, s12, 5
	s_and_b32 s15, s15, 14
	v_add_u32_e32 v0, s19, v25
	v_mad_u64_u32 v[6:7], s[20:21], s15, 17, v[0:1]
	v_mad_u64_u32 v[22:23], s[20:21], v6, s24, v[16:17]
	ds_read_b128 v[44:47], v22
	ds_read_b128 v[48:51], v22 offset:64
	s_and_b32 s15, s13, 15
	v_mad_u64_u32 v[6:7], s[20:21], s15, 17, v[0:1]
	v_mad_u64_u32 v[22:23], s[20:21], v6, s24, v[16:17]
	ds_read_b128 v[52:55], v22
	ds_read_b128 v[56:59], v22 offset:64
	global_load_dwordx4 v[60:63], v[20:21], off offset:-256
	global_load_dwordx4 v[64:67], v[20:21], off offset:-240
	global_load_dwordx4 v[68:71], v[20:21], off offset:-128
	global_load_dwordx4 v[72:75], v[20:21], off offset:-112
	global_load_dwordx4 v[76:79], v[20:21], off
	global_load_dwordx4 v[80:83], v[20:21], off offset:16
	global_load_dwordx4 v[84:87], v[20:21], off offset:128
	global_load_dwordx4 v[88:91], v[20:21], off offset:144
	global_load_dwordx4 v[92:95], v[18:19], off offset:-128
	global_load_dwordx4 v[96:99], v[18:19], off offset:-64
	global_load_dwordx4 v[100:103], v[18:19], off
	global_load_dwordx4 v[104:107], v[18:19], off offset:64
	s_add_i32 s12, s12, 4
	s_add_i32 s13, s13, 2
	s_mov_b64 s[20:21], 0x200
	v_lshl_add_u64 v[20:21], v[20:21], 0, s[20:21]
	v_lshl_add_u64 v[18:19], v[18:19], 0, s[34:35]
	s_waitcnt lgkmcnt(0)
	s_waitcnt vmcnt(10)
	v_lshlrev_b32_e32 v15, 16, v44
	v_and_b32_e32 v44, 0xffff0000, v44
	v_add_f32_e32 v15, v60, v15
	v_add_f32_e32 v44, v61, v44
	v_cvt_pk_bf16_f32 v44, v15, v44
	v_lshlrev_b32_e32 v15, 16, v45
	v_and_b32_e32 v45, 0xffff0000, v45
	v_add_f32_e32 v15, v62, v15
	v_add_f32_e32 v45, v63, v45
	v_cvt_pk_bf16_f32 v45, v15, v45
	v_lshlrev_b32_e32 v15, 16, v46
	v_and_b32_e32 v46, 0xffff0000, v46
	v_add_f32_e32 v15, v64, v15
	v_add_f32_e32 v46, v65, v46
	v_cvt_pk_bf16_f32 v46, v15, v46
	v_lshlrev_b32_e32 v15, 16, v47
	v_and_b32_e32 v47, 0xffff0000, v47
	v_add_f32_e32 v15, v66, v15
	v_add_f32_e32 v47, v67, v47
	v_cvt_pk_bf16_f32 v47, v15, v47
	s_waitcnt vmcnt(8)
	v_lshlrev_b32_e32 v15, 16, v48
	v_and_b32_e32 v48, 0xffff0000, v48
	v_add_f32_e32 v15, v68, v15
	v_add_f32_e32 v48, v69, v48
	v_cvt_pk_bf16_f32 v48, v15, v48
	v_lshlrev_b32_e32 v15, 16, v49
	v_and_b32_e32 v49, 0xffff0000, v49
	v_add_f32_e32 v15, v70, v15
	v_add_f32_e32 v49, v71, v49
	v_cvt_pk_bf16_f32 v49, v15, v49
	v_lshlrev_b32_e32 v15, 16, v50
	v_and_b32_e32 v50, 0xffff0000, v50
	v_add_f32_e32 v15, v72, v15
	v_add_f32_e32 v50, v73, v50
	v_cvt_pk_bf16_f32 v50, v15, v50
	v_lshlrev_b32_e32 v15, 16, v51
	v_and_b32_e32 v51, 0xffff0000, v51
	v_add_f32_e32 v15, v74, v15
	v_add_f32_e32 v51, v75, v51
	v_cvt_pk_bf16_f32 v51, v15, v51
	s_waitcnt vmcnt(6)
	v_lshlrev_b32_e32 v15, 16, v52
	v_and_b32_e32 v52, 0xffff0000, v52
	v_add_f32_e32 v15, v76, v15
	v_add_f32_e32 v52, v77, v52
	v_cvt_pk_bf16_f32 v52, v15, v52
	v_lshlrev_b32_e32 v15, 16, v53
	v_and_b32_e32 v53, 0xffff0000, v53
	v_add_f32_e32 v15, v78, v15
	v_add_f32_e32 v53, v79, v53
	v_cvt_pk_bf16_f32 v53, v15, v53
	v_lshlrev_b32_e32 v15, 16, v54
	v_and_b32_e32 v54, 0xffff0000, v54
	v_add_f32_e32 v15, v80, v15
	v_add_f32_e32 v54, v81, v54
	v_cvt_pk_bf16_f32 v54, v15, v54
	v_lshlrev_b32_e32 v15, 16, v55
	v_and_b32_e32 v55, 0xffff0000, v55
	v_add_f32_e32 v15, v82, v15
	v_add_f32_e32 v55, v83, v55
	v_cvt_pk_bf16_f32 v55, v15, v55
	s_waitcnt vmcnt(4)
	v_lshlrev_b32_e32 v15, 16, v56
	v_and_b32_e32 v56, 0xffff0000, v56
	v_add_f32_e32 v15, v84, v15
	v_add_f32_e32 v56, v85, v56
	v_cvt_pk_bf16_f32 v56, v15, v56
	v_lshlrev_b32_e32 v15, 16, v57
	v_and_b32_e32 v57, 0xffff0000, v57
	v_add_f32_e32 v15, v86, v15
	v_add_f32_e32 v57, v87, v57
	v_cvt_pk_bf16_f32 v57, v15, v57
	v_lshlrev_b32_e32 v15, 16, v58
	v_and_b32_e32 v58, 0xffff0000, v58
	v_add_f32_e32 v15, v88, v15
	v_add_f32_e32 v58, v89, v58
	v_cvt_pk_bf16_f32 v58, v15, v58
	v_lshlrev_b32_e32 v15, 16, v59
	v_and_b32_e32 v59, 0xffff0000, v59
	v_add_f32_e32 v15, v90, v15
	v_add_f32_e32 v59, v91, v59
	v_cvt_pk_bf16_f32 v59, v15, v59
	s_waitcnt vmcnt(3)
	s_nop 1
	v_mfma_f32_16x16x32_bf16 v[2:5], v[44:47], v[92:95], v[2:5]
	s_waitcnt vmcnt(2)
	s_nop 1
	v_mfma_f32_16x16x32_bf16 v[2:5], v[48:51], v[96:99], v[2:5]
	s_waitcnt vmcnt(1)
	s_nop 1
	v_mfma_f32_16x16x32_bf16 v[2:5], v[52:55], v[100:103], v[2:5]
	s_waitcnt vmcnt(0)
	s_nop 1
	v_mfma_f32_16x16x32_bf16 v[2:5], v[56:59], v[104:107], v[2:5]
	s_cmp_eq_u32 s12, 64
	s_cbranch_scc0 .LBB0_635
	v_lshl_add_u32 v0, v26, 11, 0
	v_lshlrev_b32_e32 v6, 2, v14
	v_lshlrev_b32_e32 v7, 2, v25
	v_add3_u32 v0, v0, v6, v7
	s_nop 2
	v_mul_f32_e32 v6, 0xbfb8aa3b, v2
	v_exp_f32_e32 v6, v6
	s_nop 0
	v_add_f32_e32 v6, 1.0, v6
	v_div_scale_f32 v7, s[12:13], v6, v6, 1.0
	v_rcp_f32_e32 v8, v7
	s_nop 0
	v_fma_f32 v9, -v7, v8, 1.0
	v_fmac_f32_e32 v8, v9, v8
	v_div_scale_f32 v9, vcc, 1.0, v6, 1.0
	v_mul_f32_e32 v10, v9, v8
	v_fma_f32 v11, -v7, v10, v9
	v_fmac_f32_e32 v10, v11, v8
	v_fma_f32 v7, -v7, v10, v9
	v_div_fmas_f32 v7, v7, v8, v10
	v_div_fixup_f32 v6, v7, v6, 1.0
	v_mul_f32_e32 v2, v2, v6
	v_mul_f32_e32 v6, 0xbfb8aa3b, v3
	v_exp_f32_e32 v6, v6
	s_nop 0
	v_add_f32_e32 v6, 1.0, v6
	v_div_scale_f32 v7, s[12:13], v6, v6, 1.0
	v_rcp_f32_e32 v8, v7
	s_nop 0
	v_fma_f32 v9, -v7, v8, 1.0
	v_fmac_f32_e32 v8, v9, v8
	v_div_scale_f32 v9, vcc, 1.0, v6, 1.0
	v_mul_f32_e32 v10, v9, v8
	v_fma_f32 v11, -v7, v10, v9
	v_fmac_f32_e32 v10, v11, v8
	v_fma_f32 v7, -v7, v10, v9
	v_div_fmas_f32 v7, v7, v8, v10
	v_div_fixup_f32 v6, v7, v6, 1.0
	v_mul_f32_e32 v3, v3, v6
	ds_write2st64_b32 v0, v2, v3 offset0:160 offset1:162
	v_mul_f32_e32 v2, 0xbfb8aa3b, v4
	v_exp_f32_e32 v2, v2
	s_nop 0
	v_add_f32_e32 v2, 1.0, v2
	v_div_scale_f32 v3, s[12:13], v2, v2, 1.0
	v_rcp_f32_e32 v6, v3
	s_nop 0
	v_fma_f32 v7, -v3, v6, 1.0
	v_fmac_f32_e32 v6, v7, v6
	v_div_scale_f32 v7, vcc, 1.0, v2, 1.0
	v_mul_f32_e32 v8, v7, v6
	v_fma_f32 v9, -v3, v8, v7
	v_fmac_f32_e32 v8, v9, v6
	v_fma_f32 v3, -v3, v8, v7
	v_div_fmas_f32 v3, v3, v6, v8
	v_div_fixup_f32 v2, v3, v2, 1.0
	v_mul_f32_e32 v3, 0xbfb8aa3b, v5
	v_exp_f32_e32 v3, v3
	v_mul_f32_e32 v2, v4, v2
	v_add_f32_e32 v3, 1.0, v3
	v_div_scale_f32 v4, s[12:13], v3, v3, 1.0
	v_rcp_f32_e32 v6, v4
	s_movk_i32 s12, 0x400
	v_fma_f32 v7, -v4, v6, 1.0
	v_fmac_f32_e32 v6, v7, v6
	v_div_scale_f32 v7, vcc, 1.0, v3, 1.0
	v_mul_f32_e32 v8, v7, v6
	v_fma_f32 v9, -v4, v8, v7
	v_fmac_f32_e32 v8, v9, v6
	v_fma_f32 v4, -v4, v8, v7
	v_div_fmas_f32 v4, v4, v6, v8
	v_div_fixup_f32 v3, v4, v3, 1.0
	v_mul_f32_e32 v3, v5, v3
	v_cmp_gt_i32_e32 vcc, s12, v24
	ds_write2st64_b32 v0, v2, v3 offset0:164 offset1:166
	s_waitcnt lgkmcnt(0)
	s_barrier
	s_and_saveexec_b64 s[12:13], vcc
	s_cbranch_execz .LBB0_645
	s_lshl_b64 s[20:21], s[92:93], 15
	s_and_b64 s[8:9], s[8:9], exec
	s_mov_b32 s8, 0x1db00000
	s_cselect_b32 s8, s8, 0x1dc00000
	s_add_u32 s8, s6, s8
	s_addc_u32 s9, s7, 0
	s_lshl_b32 s15, s18, 15
	s_add_u32 s6, s6, s15
	s_addc_u32 s7, s7, 0
	s_add_u32 s6, s6, 0x1dc80000
	s_addc_u32 s7, s7, 0
	s_lshl_b32 s14, s14, 15
	s_add_u32 s8, s8, s14
	v_and_b32_e32 v0, 7, v24
	s_addc_u32 s9, s9, 0
	v_lshlrev_b32_e32 v2, 2, v24
	v_lshlrev_b32_e32 v0, 1, v0
	v_and_b32_e32 v4, 0xfc, v2
	v_and_b32_e32 v7, 0xe0, v2
	v_lshl_add_u64 v[2:3], s[8:9], 0, v[0:1]
	s_add_u32 s8, s10, s20
	v_mov_b32_e32 v5, v1
	s_addc_u32 s9, s11, s21
	v_and_b32_e32 v6, 31, v24
	v_lshl_add_u64 v[4:5], s[8:9], 0, v[4:5]
	s_mov_b64 s[8:9], 0
	s_branch .LBB0_639
